# phase1 and final-phase prologues (adaLN shift/scale/gate vectors): hand-written, every bias and partial-sum load of a thread requested at once instead of two serial round trips, same summation order
# speedup vs baseline: 1.0021x; 1.0021x over previous
.LBB0_66:
	s_barrier
	s_mov_b64 s[44:45], exec
	s_lshr_b32 s8, s38, 7
	s_mul_i32 s46, s8, 0x1800
	s_lshl_b32 s9, s46, 2
	v_readlane_b32 s62, v250, 9
	v_readlane_b32 s63, v250, 10
	v_lshlrev_b32_e32 v72, 2, v92
	v_add_u32_e32 v73, s9, v72
	s_nop 3
	v_mov_b32_e32 v80, v72
	global_load_dword v0, v80, s[62:63]
	v_mov_b32_e32 v81, v73
	global_load_dword v1, v81, s[84:85]
	v_add_u32_e32 v80, 0xc000, v73
	global_load_dword v2, v80, s[84:85]
	v_add_u32_e32 v81, 0x18000, v73
	global_load_dword v3, v81, s[84:85]
	v_add_u32_e32 v80, 0x24000, v73
	global_load_dword v4, v80, s[84:85]
	v_add_u32_e32 v81, 0x30000, v73
	global_load_dword v5, v81, s[84:85]
	v_add_u32_e32 v80, 0x3c000, v73
	global_load_dword v6, v80, s[84:85]
	v_add_u32_e32 v81, 0x48000, v73
	global_load_dword v7, v81, s[84:85]
	v_add_u32_e32 v80, 0x54000, v73
	global_load_dword v8, v80, s[84:85]
	v_add_u32_e32 v81, 0x2000, v72
	global_load_dword v9, v81, s[62:63]
	v_add_u32_e32 v80, 0x2000, v73
	global_load_dword v10, v80, s[84:85]
	v_add_u32_e32 v81, 0xe000, v73
	global_load_dword v11, v81, s[84:85]
	v_add_u32_e32 v80, 0x1a000, v73
	global_load_dword v12, v80, s[84:85]
	v_add_u32_e32 v81, 0x26000, v73
	global_load_dword v13, v81, s[84:85]
	v_add_u32_e32 v80, 0x32000, v73
	global_load_dword v14, v80, s[84:85]
	v_add_u32_e32 v81, 0x3e000, v73
	global_load_dword v15, v81, s[84:85]
	v_add_u32_e32 v80, 0x4a000, v73
	global_load_dword v16, v80, s[84:85]
	v_add_u32_e32 v81, 0x56000, v73
	global_load_dword v17, v81, s[84:85]
	v_add_u32_e32 v80, 0x800, v72
	global_load_dword v18, v80, s[62:63]
	v_add_u32_e32 v81, 0x800, v73
	global_load_dword v19, v81, s[84:85]
	v_add_u32_e32 v80, 0xc800, v73
	global_load_dword v20, v80, s[84:85]
	v_add_u32_e32 v81, 0x18800, v73
	global_load_dword v21, v81, s[84:85]
	v_add_u32_e32 v80, 0x24800, v73
	global_load_dword v22, v80, s[84:85]
	v_add_u32_e32 v81, 0x30800, v73
	global_load_dword v23, v81, s[84:85]
	v_add_u32_e32 v80, 0x3c800, v73
	global_load_dword v24, v80, s[84:85]
	v_add_u32_e32 v81, 0x48800, v73
	global_load_dword v25, v81, s[84:85]
	v_add_u32_e32 v80, 0x54800, v73
	global_load_dword v26, v80, s[84:85]
	v_add_u32_e32 v81, 0x2800, v72
	global_load_dword v27, v81, s[62:63]
	v_add_u32_e32 v80, 0x2800, v73
	global_load_dword v28, v80, s[84:85]
	v_add_u32_e32 v81, 0xe800, v73
	global_load_dword v29, v81, s[84:85]
	v_add_u32_e32 v80, 0x1a800, v73
	global_load_dword v30, v80, s[84:85]
	v_add_u32_e32 v81, 0x26800, v73
	global_load_dword v31, v81, s[84:85]
	v_add_u32_e32 v80, 0x32800, v73
	global_load_dword v32, v80, s[84:85]
	v_add_u32_e32 v81, 0x3e800, v73
	global_load_dword v33, v81, s[84:85]
	v_add_u32_e32 v80, 0x4a800, v73
	global_load_dword v34, v80, s[84:85]
	v_add_u32_e32 v81, 0x56800, v73
	global_load_dword v35, v81, s[84:85]
	v_add_u32_e32 v80, 0x1000, v72
	global_load_dword v36, v80, s[62:63]
	v_add_u32_e32 v81, 0x1000, v73
	global_load_dword v37, v81, s[84:85]
	v_add_u32_e32 v80, 0xd000, v73
	global_load_dword v38, v80, s[84:85]
	v_add_u32_e32 v81, 0x19000, v73
	global_load_dword v39, v81, s[84:85]
	v_add_u32_e32 v80, 0x25000, v73
	global_load_dword v40, v80, s[84:85]
	v_add_u32_e32 v81, 0x31000, v73
	global_load_dword v41, v81, s[84:85]
	v_add_u32_e32 v80, 0x3d000, v73
	global_load_dword v42, v80, s[84:85]
	v_add_u32_e32 v81, 0x49000, v73
	global_load_dword v43, v81, s[84:85]
	v_add_u32_e32 v80, 0x55000, v73
	global_load_dword v44, v80, s[84:85]
	v_add_u32_e32 v81, 0x3000, v72
	global_load_dword v45, v81, s[62:63]
	v_add_u32_e32 v80, 0x3000, v73
	global_load_dword v46, v80, s[84:85]
	v_add_u32_e32 v81, 0xf000, v73
	global_load_dword v47, v81, s[84:85]
	v_add_u32_e32 v80, 0x1b000, v73
	global_load_dword v48, v80, s[84:85]
	v_add_u32_e32 v81, 0x27000, v73
	global_load_dword v49, v81, s[84:85]
	v_add_u32_e32 v80, 0x33000, v73
	global_load_dword v50, v80, s[84:85]
	v_add_u32_e32 v81, 0x3f000, v73
	global_load_dword v51, v81, s[84:85]
	v_add_u32_e32 v80, 0x4b000, v73
	global_load_dword v52, v80, s[84:85]
	v_add_u32_e32 v81, 0x57000, v73
	global_load_dword v53, v81, s[84:85]
	v_add_u32_e32 v80, 0x1800, v72
	global_load_dword v54, v80, s[62:63]
	v_add_u32_e32 v81, 0x1800, v73
	global_load_dword v55, v81, s[84:85]
	v_add_u32_e32 v80, 0xd800, v73
	global_load_dword v56, v80, s[84:85]
	v_add_u32_e32 v81, 0x19800, v73
	global_load_dword v57, v81, s[84:85]
	v_add_u32_e32 v80, 0x25800, v73
	global_load_dword v58, v80, s[84:85]
	v_add_u32_e32 v81, 0x31800, v73
	global_load_dword v59, v81, s[84:85]
	v_add_u32_e32 v80, 0x3d800, v73
	global_load_dword v60, v80, s[84:85]
	v_add_u32_e32 v81, 0x49800, v73
	global_load_dword v61, v81, s[84:85]
	v_add_u32_e32 v80, 0x55800, v73
	global_load_dword v62, v80, s[84:85]
	v_add_u32_e32 v81, 0x3800, v72
	global_load_dword v63, v81, s[62:63]
	v_add_u32_e32 v80, 0x3800, v73
	global_load_dword v64, v80, s[84:85]
	v_add_u32_e32 v81, 0xf800, v73
	global_load_dword v65, v81, s[84:85]
	v_add_u32_e32 v80, 0x1b800, v73
	global_load_dword v66, v80, s[84:85]
	v_add_u32_e32 v81, 0x27800, v73
	global_load_dword v67, v81, s[84:85]
	v_add_u32_e32 v80, 0x33800, v73
	global_load_dword v68, v80, s[84:85]
	v_add_u32_e32 v81, 0x3f800, v73
	global_load_dword v69, v81, s[84:85]
	v_add_u32_e32 v80, 0x4b800, v73
	global_load_dword v70, v80, s[84:85]
	v_add_u32_e32 v81, 0x57800, v73
	global_load_dword v71, v81, s[84:85]
	s_waitcnt vmcnt(54)
	v_add_f32_e32 v9, 1.0, v9
	v_add_f32_e32 v0, v0, v1
	v_add_f32_e32 v9, v9, v10
	v_add_f32_e32 v0, v0, v2
	v_add_f32_e32 v9, v9, v11
	v_add_f32_e32 v0, v0, v3
	v_add_f32_e32 v9, v9, v12
	v_add_f32_e32 v0, v0, v4
	v_add_f32_e32 v9, v9, v13
	v_add_f32_e32 v0, v0, v5
	v_add_f32_e32 v9, v9, v14
	v_add_f32_e32 v0, v0, v6
	v_add_f32_e32 v9, v9, v15
	v_add_f32_e32 v0, v0, v7
	v_add_f32_e32 v9, v9, v16
	v_add_f32_e32 v0, v0, v8
	v_add_f32_e32 v9, v9, v17
	ds_write_b32 v72, v0 offset:0
	ds_write_b32 v72, v9 offset:8192
	s_waitcnt vmcnt(36)
	v_add_f32_e32 v27, 1.0, v27
	v_add_f32_e32 v18, v18, v19
	v_add_f32_e32 v27, v27, v28
	v_add_f32_e32 v18, v18, v20
	v_add_f32_e32 v27, v27, v29
	v_add_f32_e32 v18, v18, v21
	v_add_f32_e32 v27, v27, v30
	v_add_f32_e32 v18, v18, v22
	v_add_f32_e32 v27, v27, v31
	v_add_f32_e32 v18, v18, v23
	v_add_f32_e32 v27, v27, v32
	v_add_f32_e32 v18, v18, v24
	v_add_f32_e32 v27, v27, v33
	v_add_f32_e32 v18, v18, v25
	v_add_f32_e32 v27, v27, v34
	v_add_f32_e32 v18, v18, v26
	v_add_f32_e32 v27, v27, v35
	ds_write_b32 v72, v18 offset:2048
	ds_write_b32 v72, v27 offset:10240
	s_waitcnt vmcnt(18)
	v_add_f32_e32 v45, 1.0, v45
	v_add_f32_e32 v36, v36, v37
	v_add_f32_e32 v45, v45, v46
	v_add_f32_e32 v36, v36, v38
	v_add_f32_e32 v45, v45, v47
	v_add_f32_e32 v36, v36, v39
	v_add_f32_e32 v45, v45, v48
	v_add_f32_e32 v36, v36, v40
	v_add_f32_e32 v45, v45, v49
	v_add_f32_e32 v36, v36, v41
	v_add_f32_e32 v45, v45, v50
	v_add_f32_e32 v36, v36, v42
	v_add_f32_e32 v45, v45, v51
	v_add_f32_e32 v36, v36, v43
	v_add_f32_e32 v45, v45, v52
	v_add_f32_e32 v36, v36, v44
	v_add_f32_e32 v45, v45, v53
	ds_write_b32 v72, v36 offset:4096
	ds_write_b32 v72, v45 offset:12288
	s_waitcnt vmcnt(0)
	v_add_f32_e32 v63, 1.0, v63
	v_add_f32_e32 v54, v54, v55
	v_add_f32_e32 v63, v63, v64
	v_add_f32_e32 v54, v54, v56
	v_add_f32_e32 v63, v63, v65
	v_add_f32_e32 v54, v54, v57
	v_add_f32_e32 v63, v63, v66
	v_add_f32_e32 v54, v54, v58
	v_add_f32_e32 v63, v63, v67
	v_add_f32_e32 v54, v54, v59
	v_add_f32_e32 v63, v63, v68
	v_add_f32_e32 v54, v54, v60
	v_add_f32_e32 v63, v63, v69
	v_add_f32_e32 v54, v54, v61
	v_add_f32_e32 v63, v63, v70
	v_add_f32_e32 v54, v54, v62
	v_add_f32_e32 v63, v63, v71
	ds_write_b32 v72, v54 offset:6144
	ds_write_b32 v72, v63 offset:14336

.LBB0_859:
	s_barrier
	s_mov_b64 s[30:31], exec
	s_lshr_b32 s10, s53, 7
	s_mul_i32 s36, s10, 0x1800
	s_lshl_b32 s11, s36, 2
	v_readlane_b32 s12, v250, 9
	v_readlane_b32 s13, v250, 10
	v_lshlrev_b32_e32 v66, 2, v164
	v_add_u32_e32 v67, s11, v66
	s_nop 3
	v_add_u32_e32 v62, 0x4000, v66
	global_load_dword v0, v62, s[12:13]
	v_add_u32_e32 v63, 0x4000, v67
	global_load_dword v1, v63, s[84:85]
	v_add_u32_e32 v62, 0x10000, v67
	global_load_dword v2, v62, s[84:85]
	v_add_u32_e32 v63, 0x1c000, v67
	global_load_dword v3, v63, s[84:85]
	v_add_u32_e32 v62, 0x28000, v67
	global_load_dword v4, v62, s[84:85]
	v_add_u32_e32 v63, 0x34000, v67
	global_load_dword v5, v63, s[84:85]
	v_add_u32_e32 v62, 0x40000, v67
	global_load_dword v6, v62, s[84:85]
	v_add_u32_e32 v63, 0x4c000, v67
	global_load_dword v7, v63, s[84:85]
	v_add_u32_e32 v62, 0x58000, v67
	global_load_dword v8, v62, s[84:85]
	v_add_u32_e32 v63, 0x4800, v66
	global_load_dword v9, v63, s[12:13]
	v_add_u32_e32 v62, 0x4800, v67
	global_load_dword v10, v62, s[84:85]
	v_add_u32_e32 v63, 0x10800, v67
	global_load_dword v11, v63, s[84:85]
	v_add_u32_e32 v62, 0x1c800, v67
	global_load_dword v12, v62, s[84:85]
	v_add_u32_e32 v63, 0x28800, v67
	global_load_dword v13, v63, s[84:85]
	v_add_u32_e32 v62, 0x34800, v67
	global_load_dword v14, v62, s[84:85]
	v_add_u32_e32 v63, 0x40800, v67
	global_load_dword v15, v63, s[84:85]
	v_add_u32_e32 v62, 0x4c800, v67
	global_load_dword v16, v62, s[84:85]
	v_add_u32_e32 v63, 0x58800, v67
	global_load_dword v17, v63, s[84:85]
	v_add_u32_e32 v62, 0x5000, v66
	global_load_dword v18, v62, s[12:13]
	v_add_u32_e32 v63, 0x5000, v67
	global_load_dword v19, v63, s[84:85]
	v_add_u32_e32 v62, 0x11000, v67
	global_load_dword v20, v62, s[84:85]
	v_add_u32_e32 v63, 0x1d000, v67
	global_load_dword v21, v63, s[84:85]
	v_add_u32_e32 v62, 0x29000, v67
	global_load_dword v22, v62, s[84:85]
	v_add_u32_e32 v63, 0x35000, v67
	global_load_dword v23, v63, s[84:85]
	v_add_u32_e32 v62, 0x41000, v67
	global_load_dword v24, v62, s[84:85]
	v_add_u32_e32 v63, 0x4d000, v67
	global_load_dword v25, v63, s[84:85]
	v_add_u32_e32 v62, 0x59000, v67
	global_load_dword v26, v62, s[84:85]
	v_add_u32_e32 v63, 0x5800, v66
	global_load_dword v27, v63, s[12:13]
	v_add_u32_e32 v62, 0x5800, v67
	global_load_dword v28, v62, s[84:85]
	v_add_u32_e32 v63, 0x11800, v67
	global_load_dword v29, v63, s[84:85]
	v_add_u32_e32 v62, 0x1d800, v67
	global_load_dword v30, v62, s[84:85]
	v_add_u32_e32 v63, 0x29800, v67
	global_load_dword v31, v63, s[84:85]
	v_add_u32_e32 v62, 0x35800, v67
	global_load_dword v58, v62, s[84:85]
	v_add_u32_e32 v63, 0x41800, v67
	global_load_dword v59, v63, s[84:85]
	v_add_u32_e32 v62, 0x4d800, v67
	global_load_dword v60, v62, s[84:85]
	v_add_u32_e32 v63, 0x59800, v67
	global_load_dword v61, v63, s[84:85]
	s_waitcnt vmcnt(27)
	v_add_f32_e32 v0, v0, v1
	v_add_f32_e32 v0, v0, v2
	v_add_f32_e32 v0, v0, v3
	v_add_f32_e32 v0, v0, v4
	v_add_f32_e32 v0, v0, v5
	v_add_f32_e32 v0, v0, v6
	v_add_f32_e32 v0, v0, v7
	v_add_f32_e32 v0, v0, v8
	ds_write_b32 v66, v0 offset:0
	s_waitcnt vmcnt(18)
	v_add_f32_e32 v9, v9, v10
	v_add_f32_e32 v9, v9, v11
	v_add_f32_e32 v9, v9, v12
	v_add_f32_e32 v9, v9, v13
	v_add_f32_e32 v9, v9, v14
	v_add_f32_e32 v9, v9, v15
	v_add_f32_e32 v9, v9, v16
	v_add_f32_e32 v9, v9, v17
	ds_write_b32 v66, v9 offset:2048
	s_waitcnt vmcnt(9)
	v_add_f32_e32 v18, v18, v19
	v_add_f32_e32 v18, v18, v20
	v_add_f32_e32 v18, v18, v21
	v_add_f32_e32 v18, v18, v22
	v_add_f32_e32 v18, v18, v23
	v_add_f32_e32 v18, v18, v24
	v_add_f32_e32 v18, v18, v25
	v_add_f32_e32 v18, v18, v26
	ds_write_b32 v66, v18 offset:4096
	s_waitcnt vmcnt(0)
	v_add_f32_e32 v27, v27, v28
	v_add_f32_e32 v27, v27, v29
	v_add_f32_e32 v27, v27, v30
	v_add_f32_e32 v27, v27, v31
	v_add_f32_e32 v27, v27, v58
	v_add_f32_e32 v27, v27, v59
	v_add_f32_e32 v27, v27, v60
	v_add_f32_e32 v27, v27, v61
	ds_write_b32 v66, v27 offset:6144
